# phase 2 items: de-serialised dependent global loads (compression bias chunks issued together, w2 copy loop with 8 loads in flight, mLSTM pre-pass V copy with 4 loads in flight)
# baseline (speedup 1.0000x reference)
.LBB0_384:
	s_or_b64 exec, exec, s[4:5]
	s_mov_b64 s[4:5], 0x1800
	v_lshl_add_u64 v[12:13], v[78:79], 0, s[4:5]
	s_mov_b64 s[4:5], 0x2800
	v_lshl_add_u64 v[16:17], v[78:79], 0, s[4:5]
	s_mov_b64 s[4:5], 0x3800
	v_lshl_add_u64 v[18:19], v[78:79], 0, s[4:5]
	global_load_dwordx4 v[8:11], v[78:79], off offset:2064
	global_load_dwordx4 v[32:35], v[78:79], off offset:2048
	global_load_dwordx4 v[36:39], v[82:83], off offset:2048
	s_nop 0
	global_load_dwordx4 v[12:15], v[12:13], off offset:16
	s_nop 0
	global_load_dwordx4 v[44:47], v[84:85], off offset:2048
	global_load_dwordx4 v[20:23], v[16:17], off offset:16
	global_load_dwordx4 v[40:43], v[86:87], off offset:2048
	s_nop 0
	global_load_dwordx4 v[16:19], v[18:19], off offset:16
	s_nop 0
	global_load_dwordx4 v[24:27], v[48:49], off offset:2064
	s_nop 0
	global_load_dwordx4 v[48:51], v[48:49], off offset:2048
	s_waitcnt vmcnt(10)
	v_lshlrev_b32_e32 v68, 16, v0
	v_and_b32_e32 v69, 0xffff0000, v0
	v_lshlrev_b32_e32 v82, 16, v60
	v_and_b32_e32 v83, 0xffff0000, v60
	v_lshlrev_b32_e32 v76, 16, v56
	v_and_b32_e32 v77, 0xffff0000, v56
	s_mov_b32 s4, 0x3db504f3
	v_lshlrev_b32_e32 v56, 16, v65
	v_lshlrev_b32_e32 v86, 16, v62
	v_and_b32_e32 v87, 0xffff0000, v62
	v_lshlrev_b32_e32 v62, 16, v59
	v_ashrrev_i32_e32 v90, 6, v80
	v_lshrrev_b32_e32 v91, 5, v104
	s_waitcnt vmcnt(0)
	v_pk_fma_f32 v[68:69], v[32:33], v[68:69], v[48:49]
	s_nop 0
	v_pk_fma_f32 v[68:69], v[36:37], v[82:83], v[68:69]
	s_nop 0
	v_pk_fma_f32 v[78:79], v[44:45], v[76:77], v[68:69]
	v_lshlrev_b32_e32 v68, 16, v64
	v_and_b32_e32 v69, 0xffff0000, v64
	v_pk_fma_f32 v[78:79], v[40:41], v[68:69], v[78:79]
	s_nop 0
	v_mul_f32_e32 v0, 0xbfb8aa3b, v78
	v_exp_f32_e32 v0, v0
	s_nop 0
	v_add_f32_e32 v0, 1.0, v0
	v_rcp_f32_e32 v84, v0
	v_mul_f32_e32 v0, 0xbfb8aa3b, v79
	v_exp_f32_e32 v0, v0
	s_nop 0
	v_add_f32_e32 v0, 1.0, v0
	v_rcp_f32_e32 v85, v0
	s_nop 0
	v_pk_mul_f32 v[78:79], v[78:79], v[84:85]
	s_nop 0
	v_pk_mul_f32 v[78:79], v[78:79], s[4:5] op_sel_hi:[1,0]
	v_lshlrev_b32_e32 v84, 16, v61
	v_cvt_pk_bf16_f32 v0, v78, v79
	v_lshlrev_b32_e32 v78, 16, v1
	v_and_b32_e32 v79, 0xffff0000, v1
	v_pk_fma_f32 v[78:79], v[34:35], v[78:79], v[50:51]
	v_and_b32_e32 v85, 0xffff0000, v61
	v_pk_fma_f32 v[60:61], v[38:39], v[84:85], v[78:79]
	v_lshlrev_b32_e32 v78, 16, v57
	v_and_b32_e32 v79, 0xffff0000, v57
	v_pk_fma_f32 v[60:61], v[46:47], v[78:79], v[60:61]
	v_and_b32_e32 v57, 0xffff0000, v65
	v_pk_fma_f32 v[60:61], v[42:43], v[56:57], v[60:61]
	s_nop 0
	v_mul_f32_e32 v1, 0xbfb8aa3b, v60
	v_exp_f32_e32 v1, v1
	s_nop 0
	v_add_f32_e32 v1, 1.0, v1
	v_rcp_f32_e32 v64, v1
	v_mul_f32_e32 v1, 0xbfb8aa3b, v61
	v_exp_f32_e32 v1, v1
	s_nop 0
	v_add_f32_e32 v1, 1.0, v1
	v_rcp_f32_e32 v65, v1
	s_nop 0
	v_pk_mul_f32 v[60:61], v[60:61], v[64:65]
	s_nop 0
	v_pk_mul_f32 v[60:61], v[60:61], s[4:5] op_sel_hi:[1,0]
	v_lshlrev_b32_e32 v64, 16, v58
	v_cvt_pk_bf16_f32 v1, v60, v61
	v_lshlrev_b32_e32 v60, 16, v2
	v_and_b32_e32 v61, 0xffff0000, v2
	v_pk_fma_f32 v[60:61], v[8:9], v[60:61], v[24:25]
	v_and_b32_e32 v65, 0xffff0000, v58
	v_pk_fma_f32 v[60:61], v[12:13], v[86:87], v[60:61]
	v_lshlrev_b32_e32 v58, 16, v67
	v_pk_fma_f32 v[88:89], v[20:21], v[64:65], v[60:61]
	v_lshlrev_b32_e32 v60, 16, v66
	v_and_b32_e32 v61, 0xffff0000, v66
	v_pk_fma_f32 v[88:89], v[16:17], v[60:61], v[88:89]
	s_nop 0
	v_mul_f32_e32 v2, 0xbfb8aa3b, v88
	v_exp_f32_e32 v2, v2
	s_nop 0
	v_add_f32_e32 v2, 1.0, v2
	v_rcp_f32_e32 v92, v2
	v_mul_f32_e32 v2, 0xbfb8aa3b, v89
	v_exp_f32_e32 v2, v2
	s_nop 0
	v_add_f32_e32 v2, 1.0, v2
	v_rcp_f32_e32 v93, v2
	s_nop 0
	v_pk_mul_f32 v[88:89], v[88:89], v[92:93]
	s_nop 0
	v_pk_mul_f32 v[88:89], v[88:89], s[4:5] op_sel_hi:[1,0]
	s_nop 0
	v_cvt_pk_bf16_f32 v2, v88, v89
	v_lshlrev_b32_e32 v88, 16, v3
	v_and_b32_e32 v89, 0xffff0000, v3
	v_pk_fma_f32 v[92:93], v[10:11], v[88:89], v[26:27]
	v_lshlrev_b32_e32 v88, 16, v63
	v_and_b32_e32 v89, 0xffff0000, v63
	v_pk_fma_f32 v[92:93], v[14:15], v[88:89], v[92:93]
	v_and_b32_e32 v63, 0xffff0000, v59
	v_pk_fma_f32 v[92:93], v[22:23], v[62:63], v[92:93]
	v_and_b32_e32 v59, 0xffff0000, v67
	v_pk_fma_f32 v[66:67], v[18:19], v[58:59], v[92:93]
	s_nop 0
	v_mul_f32_e32 v3, 0xbfb8aa3b, v66
	v_exp_f32_e32 v3, v3
	s_nop 0
	v_add_f32_e32 v3, 1.0, v3
	v_rcp_f32_e32 v92, v3
	v_mul_f32_e32 v3, 0xbfb8aa3b, v67
	v_exp_f32_e32 v3, v3
	s_nop 0
	v_add_f32_e32 v3, 1.0, v3
	v_rcp_f32_e32 v93, v3
	s_nop 0
	v_pk_mul_f32 v[66:67], v[66:67], v[92:93]
	s_nop 0
	v_pk_mul_f32 v[66:67], v[66:67], s[4:5] op_sel_hi:[1,0]
	s_nop 0
	v_cvt_pk_bf16_f32 v3, v66, v67
	ds_write_b128 v105, v[0:3] offset:17408
	v_pk_fma_f32 v[0:1], v[32:33], v[82:83], v[48:49]
	s_nop 0
	v_pk_fma_f32 v[0:1], v[36:37], v[76:77], v[0:1]
	s_nop 0
	v_pk_fma_f32 v[2:3], v[44:45], v[68:69], v[0:1]
	v_lshlrev_b32_e32 v0, 16, v52
	v_and_b32_e32 v1, 0xffff0000, v52
	v_pk_fma_f32 v[2:3], v[40:41], v[0:1], v[2:3]
	s_nop 0
	v_mul_f32_e32 v52, 0xbfb8aa3b, v2
	v_exp_f32_e32 v52, v52
	s_nop 0
	v_add_f32_e32 v52, 1.0, v52
	v_rcp_f32_e32 v66, v52
	v_mul_f32_e32 v52, 0xbfb8aa3b, v3
	v_exp_f32_e32 v52, v52
	s_nop 0
	v_add_f32_e32 v52, 1.0, v52
	v_rcp_f32_e32 v67, v52
	s_nop 0
	v_pk_mul_f32 v[2:3], v[2:3], v[66:67]
	s_nop 0
	v_pk_mul_f32 v[2:3], v[2:3], s[4:5] op_sel_hi:[1,0]
	s_nop 0
	v_cvt_pk_bf16_f32 v82, v2, v3
	v_pk_fma_f32 v[2:3], v[34:35], v[84:85], v[50:51]
	s_nop 0
	v_pk_fma_f32 v[2:3], v[38:39], v[78:79], v[2:3]
	s_nop 0
	v_pk_fma_f32 v[66:67], v[46:47], v[56:57], v[2:3]
	v_lshlrev_b32_e32 v2, 16, v53
	v_and_b32_e32 v3, 0xffff0000, v53
	v_pk_fma_f32 v[52:53], v[42:43], v[2:3], v[66:67]
	s_nop 0
	v_mul_f32_e32 v66, 0xbfb8aa3b, v52
	v_mul_f32_e32 v67, 0xbfb8aa3b, v53
	v_exp_f32_e32 v66, v66
	v_exp_f32_e32 v67, v67
	v_add_f32_e32 v66, 1.0, v66
	v_add_f32_e32 v67, 1.0, v67
	v_rcp_f32_e32 v66, v66
	v_rcp_f32_e32 v67, v67
	s_nop 0
	v_pk_mul_f32 v[52:53], v[52:53], v[66:67]
	s_nop 0
	v_pk_mul_f32 v[52:53], v[52:53], s[4:5] op_sel_hi:[1,0]
	s_nop 0
	v_cvt_pk_bf16_f32 v83, v52, v53
	v_pk_fma_f32 v[52:53], v[8:9], v[86:87], v[24:25]
	s_nop 0
	v_pk_fma_f32 v[52:53], v[12:13], v[64:65], v[52:53]
	v_pk_fma_f32 v[64:65], v[8:9], v[64:65], v[24:25]
	v_pk_fma_f32 v[66:67], v[20:21], v[60:61], v[52:53]
	v_lshlrev_b32_e32 v52, 16, v54
	v_and_b32_e32 v53, 0xffff0000, v54
	v_pk_fma_f32 v[66:67], v[16:17], v[52:53], v[66:67]
	v_pk_fma_f32 v[64:65], v[12:13], v[60:61], v[64:65]
	v_mul_f32_e32 v54, 0xbfb8aa3b, v66
	v_exp_f32_e32 v54, v54
	v_pk_fma_f32 v[64:65], v[20:21], v[52:53], v[64:65]
	v_add_f32_e32 v54, 1.0, v54
	v_rcp_f32_e32 v84, v54
	v_mul_f32_e32 v54, 0xbfb8aa3b, v67
	v_exp_f32_e32 v54, v54
	s_nop 0
	v_add_f32_e32 v54, 1.0, v54
	v_rcp_f32_e32 v85, v54
	v_lshlrev_b32_e32 v54, 16, v55
	v_and_b32_e32 v55, 0xffff0000, v55
	v_pk_mul_f32 v[66:67], v[66:67], v[84:85]
	s_nop 0
	v_pk_mul_f32 v[66:67], v[66:67], s[4:5] op_sel_hi:[1,0]
	s_nop 0
	v_cvt_pk_bf16_f32 v84, v66, v67
	v_pk_fma_f32 v[66:67], v[10:11], v[88:89], v[26:27]
	s_nop 0
	v_pk_fma_f32 v[66:67], v[14:15], v[62:63], v[66:67]
	v_pk_fma_f32 v[62:63], v[10:11], v[62:63], v[26:27]
	v_pk_fma_f32 v[66:67], v[22:23], v[58:59], v[66:67]
	v_pk_fma_f32 v[62:63], v[14:15], v[58:59], v[62:63]
	v_pk_fma_f32 v[66:67], v[18:19], v[54:55], v[66:67]
	v_pk_fma_f32 v[62:63], v[22:23], v[54:55], v[62:63]
	v_mul_f32_e32 v85, 0xbfb8aa3b, v66
	v_exp_f32_e32 v85, v85
	s_nop 0
	v_add_f32_e32 v85, 1.0, v85
	v_rcp_f32_e32 v86, v85
	v_mul_f32_e32 v85, 0xbfb8aa3b, v67
	v_exp_f32_e32 v85, v85
	s_nop 0
	v_add_f32_e32 v85, 1.0, v85
	v_rcp_f32_e32 v87, v85
	s_nop 0
	v_pk_mul_f32 v[66:67], v[66:67], v[86:87]
	s_nop 0
	v_pk_mul_f32 v[66:67], v[66:67], s[4:5] op_sel_hi:[1,0]
	s_nop 0
	v_cvt_pk_bf16_f32 v85, v66, v67
	v_pk_fma_f32 v[66:67], v[32:33], v[76:77], v[48:49]
	v_lshlrev_b32_e32 v76, 16, v28
	v_pk_fma_f32 v[66:67], v[36:37], v[68:69], v[66:67]
	v_and_b32_e32 v77, 0xffff0000, v28
	v_pk_fma_f32 v[66:67], v[44:45], v[0:1], v[66:67]
	ds_write_b128 v105, v[82:85] offset:17680
	v_pk_fma_f32 v[66:67], v[40:41], v[76:77], v[66:67]
	s_nop 0
	v_mul_f32_e32 v28, 0xbfb8aa3b, v66
	v_exp_f32_e32 v28, v28
	s_nop 0
	v_add_f32_e32 v28, 1.0, v28
	v_rcp_f32_e32 v82, v28
	v_mul_f32_e32 v28, 0xbfb8aa3b, v67
	v_exp_f32_e32 v28, v28
	s_nop 0
	v_add_f32_e32 v28, 1.0, v28
	v_rcp_f32_e32 v83, v28
	s_nop 0
	v_pk_mul_f32 v[66:67], v[66:67], v[82:83]
	s_nop 0
	v_pk_mul_f32 v[66:67], v[66:67], s[4:5] op_sel_hi:[1,0]
	s_nop 0
	v_cvt_pk_bf16_f32 v28, v66, v67
	v_pk_fma_f32 v[66:67], v[34:35], v[78:79], v[50:51]
	v_lshlrev_b32_e32 v78, 16, v29
	v_pk_fma_f32 v[66:67], v[38:39], v[56:57], v[66:67]
	v_and_b32_e32 v79, 0xffff0000, v29
	v_pk_fma_f32 v[66:67], v[46:47], v[2:3], v[66:67]
	s_nop 0
	v_pk_fma_f32 v[66:67], v[42:43], v[78:79], v[66:67]
	s_nop 0
	v_mul_f32_e32 v29, 0xbfb8aa3b, v66
	v_exp_f32_e32 v29, v29
	s_nop 0
	v_add_f32_e32 v29, 1.0, v29
	v_rcp_f32_e32 v82, v29
	v_mul_f32_e32 v29, 0xbfb8aa3b, v67
	v_exp_f32_e32 v29, v29
	s_nop 0
	v_add_f32_e32 v29, 1.0, v29
	v_rcp_f32_e32 v83, v29
	s_nop 0
	v_pk_mul_f32 v[66:67], v[66:67], v[82:83]
	s_nop 0
	v_pk_mul_f32 v[66:67], v[66:67], s[4:5] op_sel_hi:[1,0]
	s_nop 0
	v_cvt_pk_bf16_f32 v29, v66, v67
	v_lshlrev_b32_e32 v66, 16, v30
	v_and_b32_e32 v67, 0xffff0000, v30
	v_pk_fma_f32 v[64:65], v[16:17], v[66:67], v[64:65]
	s_nop 0
	v_mul_f32_e32 v30, 0xbfb8aa3b, v64
	v_exp_f32_e32 v30, v30
	s_nop 0
	v_add_f32_e32 v30, 1.0, v30
	v_rcp_f32_e32 v82, v30
	v_mul_f32_e32 v30, 0xbfb8aa3b, v65
	v_exp_f32_e32 v30, v30
	s_nop 0
	v_add_f32_e32 v30, 1.0, v30
	v_rcp_f32_e32 v83, v30
	s_nop 0
	v_pk_mul_f32 v[64:65], v[64:65], v[82:83]
	s_nop 0
	v_pk_mul_f32 v[64:65], v[64:65], s[4:5] op_sel_hi:[1,0]
	s_nop 0
	v_cvt_pk_bf16_f32 v30, v64, v65
	v_lshlrev_b32_e32 v64, 16, v31
	v_and_b32_e32 v65, 0xffff0000, v31
	v_pk_fma_f32 v[62:63], v[18:19], v[64:65], v[62:63]
	s_nop 0
	v_mul_f32_e32 v31, 0xbfb8aa3b, v62
	v_exp_f32_e32 v31, v31
	s_nop 0
	v_add_f32_e32 v31, 1.0, v31
	v_rcp_f32_e32 v82, v31
	v_mul_f32_e32 v31, 0xbfb8aa3b, v63
	v_exp_f32_e32 v31, v31
	s_nop 0
	v_add_f32_e32 v31, 1.0, v31
	v_rcp_f32_e32 v83, v31
	s_nop 0
	v_pk_mul_f32 v[62:63], v[62:63], v[82:83]
	s_nop 0
	v_pk_mul_f32 v[62:63], v[62:63], s[4:5] op_sel_hi:[1,0]
	s_nop 0
	v_cvt_pk_bf16_f32 v31, v62, v63
	ds_write_b128 v105, v[28:31] offset:17952
	v_pk_fma_f32 v[28:29], v[32:33], v[68:69], v[48:49]
	v_lshlrev_b32_e32 v31, 4, v91
	v_pk_fma_f32 v[0:1], v[36:37], v[0:1], v[28:29]
	v_lshlrev_b32_e32 v28, 16, v4
	v_pk_fma_f32 v[0:1], v[44:45], v[76:77], v[0:1]
	v_and_b32_e32 v29, 0xffff0000, v4
	v_pk_fma_f32 v[0:1], v[40:41], v[28:29], v[0:1]
	s_nop 0
	v_mul_f32_e32 v4, 0xbfb8aa3b, v0
	v_exp_f32_e32 v4, v4
	s_nop 0
	v_add_f32_e32 v4, 1.0, v4
	v_rcp_f32_e32 v28, v4
	v_mul_f32_e32 v4, 0xbfb8aa3b, v1
	v_exp_f32_e32 v4, v4
	s_nop 0
	v_add_f32_e32 v4, 1.0, v4
	v_rcp_f32_e32 v29, v4
	v_lshlrev_b32_e32 v4, 16, v5
	v_and_b32_e32 v5, 0xffff0000, v5
	v_pk_mul_f32 v[0:1], v[0:1], v[28:29]
	v_pk_fma_f32 v[28:29], v[34:35], v[56:57], v[50:51]
	v_pk_mul_f32 v[0:1], v[0:1], s[4:5] op_sel_hi:[1,0]
	v_pk_fma_f32 v[2:3], v[38:39], v[2:3], v[28:29]
	v_cvt_pk_bf16_f32 v0, v0, v1
	v_pk_fma_f32 v[2:3], v[46:47], v[78:79], v[2:3]
	v_lshlrev_b32_e32 v28, 2, v91
	v_pk_fma_f32 v[2:3], v[42:43], v[4:5], v[2:3]
	s_nop 0
	v_mul_f32_e32 v1, 0xbfb8aa3b, v2
	v_exp_f32_e32 v1, v1
	s_nop 0
	v_add_f32_e32 v1, 1.0, v1
	v_rcp_f32_e32 v4, v1
	v_mul_f32_e32 v1, 0xbfb8aa3b, v3
	v_exp_f32_e32 v1, v1
	s_nop 0
	v_add_f32_e32 v1, 1.0, v1
	v_rcp_f32_e32 v5, v1
	s_nop 0
	v_pk_mul_f32 v[2:3], v[2:3], v[4:5]
	s_nop 0
	v_pk_mul_f32 v[2:3], v[2:3], s[4:5] op_sel_hi:[1,0]
	v_lshlrev_b32_e32 v4, 16, v6
	v_cvt_pk_bf16_f32 v1, v2, v3
	v_pk_fma_f32 v[2:3], v[8:9], v[60:61], v[24:25]
	v_and_b32_e32 v5, 0xffff0000, v6
	v_pk_fma_f32 v[2:3], v[12:13], v[52:53], v[2:3]
	v_lshlrev_b32_e32 v6, 16, v7
	v_pk_fma_f32 v[2:3], v[20:21], v[66:67], v[2:3]
	v_and_b32_e32 v7, 0xffff0000, v7
	v_pk_fma_f32 v[2:3], v[16:17], v[4:5], v[2:3]
	v_lshlrev_b32_e32 v16, 3, v91
	v_mul_f32_e32 v4, 0xbfb8aa3b, v2
	v_mul_f32_e32 v5, 0xbfb8aa3b, v3
	v_exp_f32_e32 v4, v4
	v_exp_f32_e32 v5, v5
	v_add_f32_e32 v4, 1.0, v4
	v_add_f32_e32 v5, 1.0, v5
	v_rcp_f32_e32 v4, v4
	v_rcp_f32_e32 v5, v5
	s_nop 0
	v_pk_mul_f32 v[2:3], v[2:3], v[4:5]
	v_pk_fma_f32 v[4:5], v[10:11], v[58:59], v[26:27]
	v_pk_mul_f32 v[2:3], v[2:3], s[4:5] op_sel_hi:[1,0]
	v_pk_fma_f32 v[4:5], v[14:15], v[54:55], v[4:5]
	v_cvt_pk_bf16_f32 v2, v2, v3
	v_pk_fma_f32 v[4:5], v[22:23], v[64:65], v[4:5]
	s_nop 0
	v_pk_fma_f32 v[4:5], v[18:19], v[6:7], v[4:5]
	s_nop 0
	v_mul_f32_e32 v3, 0xbfb8aa3b, v4
	v_exp_f32_e32 v3, v3
	s_nop 0
	v_add_f32_e32 v3, 1.0, v3
	v_rcp_f32_e32 v6, v3
	v_mul_f32_e32 v3, 0xbfb8aa3b, v5
	v_exp_f32_e32 v3, v3
	s_nop 0
	v_add_f32_e32 v3, 1.0, v3
	v_rcp_f32_e32 v7, v3
	s_nop 0
	v_pk_mul_f32 v[4:5], v[4:5], v[6:7]
	s_nop 0
	v_pk_mul_f32 v[4:5], v[4:5], s[4:5] op_sel_hi:[1,0]
	s_movk_i32 s4, 0x3000
	v_cvt_pk_bf16_f32 v3, v4, v5
	ds_write_b128 v105, v[0:3] offset:18224
	global_load_dwordx4 v[0:3], v[70:71], off offset:2048
	v_or_b32_e32 v4, 3, v81
	v_mul_lo_u32 v4, v4, s48
	v_add_u32_e32 v30, v75, v4
	v_add_co_u32_e32 v152, vcc, s4, v70
	s_nop 1
	v_addc_co_u32_e32 v153, vcc, 0, v71, vcc
	global_load_dwordx4 v[152:155], v[152:153], off
	v_add_co_u32_e32 v156, vcc, 0x5000, v70
	s_nop 1
	v_addc_co_u32_e32 v157, vcc, 0, v71, vcc
	global_load_dwordx4 v[156:159], v[156:157], off offset:2048
	v_add_co_u32_e32 v160, vcc, 0x8000, v70
	s_nop 1
	v_addc_co_u32_e32 v161, vcc, 0, v71, vcc
	global_load_dwordx4 v[160:163], v[160:161], off
	v_cmp_lt_i32_e32 vcc, 2, v90
	s_waitcnt vmcnt(3)
	ds_write_b128 v105, v[0:3] offset:34816
	s_waitcnt vmcnt(2)
	ds_write_b128 v105, v[152:155] offset:35088
	s_waitcnt vmcnt(1)
	ds_write_b128 v105, v[156:159] offset:35360
	s_waitcnt vmcnt(0)
	ds_write_b128 v30, v[160:163] offset:34816
	s_waitcnt lgkmcnt(0)
	s_barrier
	s_and_saveexec_b64 s[4:5], vcc
	s_xor_b64 s[4:5], exec, s[4:5]
	s_cbranch_execz .LBB0_386
	v_lshrrev_b32_e32 v0, 1, v104
	v_lshlrev_b32_e32 v1, 5, v80
	s_mov_b32 s8, s3
	s_mov_b32 s9, s3
	v_mul_u32_u24_e32 v0, 0x90, v0
	v_and_b32_e32 v1, 32, v1
	s_mov_b32 s10, s3
	s_mov_b32 s11, s3
	v_mov_b64_e32 v[2:3], s[8:9]
	v_add3_u32 v0, 0, v0, v1
	v_mov_b64_e32 v[4:5], s[10:11]
	ds_write_b128 v0, v[2:5] offset:52288
	ds_write_b128 v0, v[2:5] offset:52304
	v_lshlrev_b32_e32 v16, 3, v91
	v_lshlrev_b32_e32 v31, 4, v91
	v_lshlrev_b32_e32 v28, 2, v91

.LBB0_400:
	s_lshl_b32 s0, s0, 7
	s_ashr_i32 s1, s0, 31
	s_waitcnt vmcnt(5)
	v_and_b32_e32 v32, 64, v80
	s_lshl_b64 s[0:1], s[0:1], 2
	v_lshrrev_b32_e32 v34, 3, v80
	v_and_b32_e32 v33, 31, v80
	s_add_u32 s6, s68, s0
	s_waitcnt vmcnt(3)
	v_and_or_b32 v40, v34, 4, v32
	v_ashrrev_i32_e32 v32, 2, v80
	s_mov_b32 s0, 0xfffffe0
	v_and_or_b32 v33, v32, s0, v33
	s_addc_u32 s7, s69, s1
	v_mul_lo_u32 v41, v33, s48
	v_lshlrev_b32_e32 v33, 2, v40
	global_load_dwordx4 v[152:155], v33, s[6:7]
	global_load_dwordx4 v[156:159], v33, s[6:7] offset:32
	global_load_dwordx4 v[160:163], v33, s[6:7] offset:64
	global_load_dwordx4 v[166:169], v33, s[6:7] offset:96
	global_load_dwordx4 v[170:173], v33, s[6:7] offset:128
	global_load_dwordx4 v[174:177], v33, s[6:7] offset:160
	global_load_dwordx4 v[184:187], v33, s[6:7] offset:192
	global_load_dwordx4 v[188:191], v33, s[6:7] offset:224
	s_movk_i32 s0, 0x7ff
	v_cmp_lt_i32_e32 vcc, s0, v80
	s_waitcnt vmcnt(0)
	v_pk_add_f32 v[16:17], v[16:17], v[152:153]
	s_nop 0
	v_mul_f32_e32 v34, 0xbfb8aa3b, v16
	v_mul_f32_e32 v35, 0xbfb8aa3b, v17
	v_exp_f32_e32 v34, v34
	v_exp_f32_e32 v35, v35
	v_add_f32_e32 v34, 1.0, v34
	v_add_f32_e32 v35, 1.0, v35
	v_rcp_f32_e32 v34, v34
	v_rcp_f32_e32 v35, v35
	s_nop 0
	v_pk_mul_f32 v[16:17], v[16:17], v[34:35]
	s_nop 0
	v_cvt_pk_bf16_f32 v38, v16, v17
	v_pk_add_f32 v[16:17], v[18:19], v[154:155]
	v_mul_f32_e32 v18, 0xbfb8aa3b, v16
	v_mul_f32_e32 v19, 0xbfb8aa3b, v17
	v_exp_f32_e32 v18, v18
	v_exp_f32_e32 v19, v19
	v_add_f32_e32 v18, 1.0, v18
	v_add_f32_e32 v19, 1.0, v19
	v_rcp_f32_e32 v18, v18
	v_rcp_f32_e32 v19, v19
	s_nop 0
	v_pk_mul_f32 v[16:17], v[16:17], v[18:19]
	s_nop 0
	v_cvt_pk_bf16_f32 v39, v16, v17
	v_lshlrev_b32_e32 v16, 1, v40
	v_add3_u32 v16, 0, v41, v16
	v_pk_add_f32 v[18:19], v[20:21], v[156:157]
	s_nop 0
	v_mul_f32_e32 v17, 0xbfb8aa3b, v18
	v_exp_f32_e32 v17, v17
	s_nop 0
	v_add_f32_e32 v17, 1.0, v17
	v_rcp_f32_e32 v20, v17
	v_mul_f32_e32 v17, 0xbfb8aa3b, v19
	v_exp_f32_e32 v17, v17
	s_nop 0
	v_add_f32_e32 v17, 1.0, v17
	v_rcp_f32_e32 v21, v17
	s_nop 0
	v_pk_mul_f32 v[18:19], v[18:19], v[20:21]
	v_pk_add_f32 v[20:21], v[22:23], v[158:159]
	v_cvt_pk_bf16_f32 v18, v18, v19
	v_mul_f32_e32 v17, 0xbfb8aa3b, v20
	v_exp_f32_e32 v17, v17
	s_nop 0
	v_add_f32_e32 v17, 1.0, v17
	v_rcp_f32_e32 v22, v17
	v_mul_f32_e32 v17, 0xbfb8aa3b, v21
	v_exp_f32_e32 v17, v17
	s_nop 0
	v_add_f32_e32 v17, 1.0, v17
	v_rcp_f32_e32 v23, v17
	s_nop 0
	v_pk_mul_f32 v[20:21], v[20:21], v[22:23]
	s_nop 0
	v_cvt_pk_bf16_f32 v19, v20, v21
	ds_write2_b64 v16, v[38:39], v[18:19] offset1:2
	v_pk_add_f32 v[18:19], v[24:25], v[160:161]
	s_nop 0
	v_mul_f32_e32 v17, 0xbfb8aa3b, v18
	v_exp_f32_e32 v17, v17
	s_nop 0
	v_add_f32_e32 v17, 1.0, v17
	v_rcp_f32_e32 v22, v17
	v_mul_f32_e32 v17, 0xbfb8aa3b, v19
	v_exp_f32_e32 v17, v17
	s_nop 0
	v_add_f32_e32 v17, 1.0, v17
	v_rcp_f32_e32 v23, v17
	s_nop 0
	v_pk_mul_f32 v[18:19], v[18:19], v[22:23]
	s_nop 0
	v_cvt_pk_bf16_f32 v22, v18, v19
	v_pk_add_f32 v[18:19], v[26:27], v[162:163]
	s_nop 0
	v_mul_f32_e32 v17, 0xbfb8aa3b, v18
	v_exp_f32_e32 v17, v17
	s_nop 0
	v_add_f32_e32 v17, 1.0, v17
	v_rcp_f32_e32 v20, v17
	v_mul_f32_e32 v17, 0xbfb8aa3b, v19
	v_exp_f32_e32 v17, v17
	s_nop 0
	v_add_f32_e32 v17, 1.0, v17
	v_rcp_f32_e32 v21, v17
	s_nop 0
	v_pk_mul_f32 v[18:19], v[18:19], v[20:21]
	s_nop 0
	v_cvt_pk_bf16_f32 v23, v18, v19
	v_pk_add_f32 v[18:19], v[28:29], v[166:167]
	s_nop 0
	v_mul_f32_e32 v17, 0xbfb8aa3b, v18
	v_exp_f32_e32 v17, v17
	v_pk_add_f32 v[20:21], v[30:31], v[168:169]
	v_add_f32_e32 v17, 1.0, v17
	v_rcp_f32_e32 v24, v17
	v_mul_f32_e32 v17, 0xbfb8aa3b, v19
	v_exp_f32_e32 v17, v17
	s_nop 0
	v_add_f32_e32 v17, 1.0, v17
	v_rcp_f32_e32 v25, v17
	v_mul_f32_e32 v17, 0xbfb8aa3b, v20
	v_exp_f32_e32 v17, v17
	v_pk_mul_f32 v[18:19], v[18:19], v[24:25]
	s_nop 0
	v_cvt_pk_bf16_f32 v18, v18, v19
	v_add_f32_e32 v17, 1.0, v17
	v_rcp_f32_e32 v24, v17
	v_mul_f32_e32 v17, 0xbfb8aa3b, v21
	v_exp_f32_e32 v17, v17
	s_nop 0
	v_add_f32_e32 v17, 1.0, v17
	v_rcp_f32_e32 v25, v17
	s_nop 0
	v_pk_mul_f32 v[20:21], v[20:21], v[24:25]
	s_nop 0
	v_cvt_pk_bf16_f32 v19, v20, v21
	ds_write2_b64 v16, v[22:23], v[18:19] offset0:4 offset1:6
	v_pk_add_f32 v[0:1], v[0:1], v[170:171]
	s_nop 0
	v_mul_f32_e32 v17, 0xbfb8aa3b, v0
	v_exp_f32_e32 v17, v17
	s_nop 0
	v_add_f32_e32 v17, 1.0, v17
	v_rcp_f32_e32 v18, v17
	v_mul_f32_e32 v17, 0xbfb8aa3b, v1
	v_exp_f32_e32 v17, v17
	s_nop 0
	v_add_f32_e32 v17, 1.0, v17
	v_rcp_f32_e32 v19, v17
	s_nop 0
	v_pk_mul_f32 v[0:1], v[0:1], v[18:19]
	s_nop 0
	v_cvt_pk_bf16_f32 v18, v0, v1
	v_pk_add_f32 v[0:1], v[2:3], v[172:173]
	s_nop 0
	v_mul_f32_e32 v2, 0xbfb8aa3b, v0
	v_mul_f32_e32 v3, 0xbfb8aa3b, v1
	v_exp_f32_e32 v2, v2
	v_exp_f32_e32 v3, v3
	v_add_f32_e32 v2, 1.0, v2
	v_add_f32_e32 v3, 1.0, v3
	v_rcp_f32_e32 v2, v2
	v_rcp_f32_e32 v3, v3
	s_nop 0
	v_pk_mul_f32 v[0:1], v[0:1], v[2:3]
	s_nop 0
	v_cvt_pk_bf16_f32 v19, v0, v1
	v_pk_add_f32 v[0:1], v[4:5], v[174:175]
	s_nop 0
	v_mul_f32_e32 v4, 0xbfb8aa3b, v0
	v_mul_f32_e32 v5, 0xbfb8aa3b, v1
	v_exp_f32_e32 v4, v4
	v_exp_f32_e32 v5, v5
	v_pk_add_f32 v[2:3], v[6:7], v[176:177]
	v_add_f32_e32 v4, 1.0, v4
	v_add_f32_e32 v5, 1.0, v5
	v_rcp_f32_e32 v4, v4
	v_rcp_f32_e32 v5, v5
	s_nop 0
	v_pk_mul_f32 v[0:1], v[0:1], v[4:5]
	s_nop 0
	v_cvt_pk_bf16_f32 v0, v0, v1
	v_mul_f32_e32 v1, 0xbfb8aa3b, v2
	v_exp_f32_e32 v1, v1
	s_nop 0
	v_add_f32_e32 v1, 1.0, v1
	v_rcp_f32_e32 v4, v1
	v_mul_f32_e32 v1, 0xbfb8aa3b, v3
	v_exp_f32_e32 v1, v1
	s_nop 0
	v_add_f32_e32 v1, 1.0, v1
	v_rcp_f32_e32 v5, v1
	s_nop 0
	v_pk_mul_f32 v[2:3], v[2:3], v[4:5]
	s_nop 0
	v_cvt_pk_bf16_f32 v1, v2, v3
	ds_write2_b64 v16, v[18:19], v[0:1] offset0:8 offset1:10
	v_pk_add_f32 v[0:1], v[8:9], v[184:185]
	s_nop 0
	v_mul_f32_e32 v4, 0xbfb8aa3b, v0
	v_mul_f32_e32 v5, 0xbfb8aa3b, v1
	v_exp_f32_e32 v4, v4
	v_exp_f32_e32 v5, v5
	v_add_f32_e32 v4, 1.0, v4
	v_add_f32_e32 v5, 1.0, v5
	v_rcp_f32_e32 v4, v4
	v_rcp_f32_e32 v5, v5
	s_nop 0
	v_pk_mul_f32 v[0:1], v[0:1], v[4:5]
	s_nop 0
	v_cvt_pk_bf16_f32 v4, v0, v1
	v_pk_add_f32 v[0:1], v[10:11], v[186:187]
	s_nop 0
	v_mul_f32_e32 v2, 0xbfb8aa3b, v0
	v_mul_f32_e32 v3, 0xbfb8aa3b, v1
	v_exp_f32_e32 v2, v2
	v_exp_f32_e32 v3, v3
	v_add_f32_e32 v2, 1.0, v2
	v_add_f32_e32 v3, 1.0, v3
	v_rcp_f32_e32 v2, v2
	v_rcp_f32_e32 v3, v3
	s_nop 0
	v_pk_mul_f32 v[0:1], v[0:1], v[2:3]
	s_nop 0
	v_cvt_pk_bf16_f32 v5, v0, v1
	v_pk_add_f32 v[0:1], v[12:13], v[188:189]
	s_nop 0
	v_mul_f32_e32 v6, 0xbfb8aa3b, v0
	v_mul_f32_e32 v7, 0xbfb8aa3b, v1
	v_exp_f32_e32 v6, v6
	v_exp_f32_e32 v7, v7
	v_pk_add_f32 v[2:3], v[14:15], v[190:191]
	v_add_f32_e32 v6, 1.0, v6
	v_add_f32_e32 v7, 1.0, v7
	v_rcp_f32_e32 v6, v6
	v_rcp_f32_e32 v7, v7
	s_nop 0
	v_pk_mul_f32 v[0:1], v[0:1], v[6:7]
	s_nop 0
	v_cvt_pk_bf16_f32 v0, v0, v1
	v_mul_f32_e32 v1, 0xbfb8aa3b, v2
	v_exp_f32_e32 v1, v1
	s_nop 0
	v_add_f32_e32 v1, 1.0, v1
	v_rcp_f32_e32 v6, v1
	v_mul_f32_e32 v1, 0xbfb8aa3b, v3
	v_exp_f32_e32 v1, v1
	s_nop 0
	v_add_f32_e32 v1, 1.0, v1
	v_rcp_f32_e32 v7, v1
	s_nop 0
	v_pk_mul_f32 v[2:3], v[2:3], v[6:7]
	s_nop 0
	v_cvt_pk_bf16_f32 v1, v2, v3
	ds_write2_b64 v16, v[4:5], v[0:1] offset0:12 offset1:14
	v_lshlrev_b32_e32 v16, 4, v80
	s_and_saveexec_b64 s[0:1], vcc
	s_xor_b64 s[0:1], exec, s[0:1]
	v_lshlrev_b32_e32 v16, 4, v80
	s_andn2_saveexec_b64 s[6:7], s[0:1]
	s_cbranch_execz .LBB0_406
	s_and_b64 s[0:1], s[4:5], exec
	s_cselect_b32 s0, 48, 0x48
	s_add_u32 s0, s52, s0
	s_addc_u32 s1, s53, 0
	s_load_dwordx2 s[0:1], s[0:1], 0x0
	v_readlane_b32 s2, v249, 16
	v_ashrrev_i32_e32 v81, 31, v80
	v_add_u32_e32 v3, 0xffffff00, v80
	v_add_u32_e32 v2, s2, v16
	s_waitcnt lgkmcnt(0)
	v_lshl_add_u64 v[0:1], v[80:81], 4, s[0:1]
	s_mov_b64 s[8:9], 0
.LBB0_404:
	global_load_dwordx4 v[64:67], v[0:1], off
	v_lshl_add_u64 v[0:1], v[0:1], 0, s[18:19]
	global_load_dwordx4 v[68:71], v[0:1], off
	v_lshl_add_u64 v[0:1], v[0:1], 0, s[18:19]
	global_load_dwordx4 v[76:79], v[0:1], off
	v_lshl_add_u64 v[0:1], v[0:1], 0, s[18:19]
	global_load_dwordx4 v[84:87], v[0:1], off
	v_lshl_add_u64 v[0:1], v[0:1], 0, s[18:19]
	global_load_dwordx4 v[88:91], v[0:1], off
	v_lshl_add_u64 v[0:1], v[0:1], 0, s[18:19]
	global_load_dwordx4 v[92:95], v[0:1], off
	v_lshl_add_u64 v[0:1], v[0:1], 0, s[18:19]
	global_load_dwordx4 v[128:131], v[0:1], off
	v_lshl_add_u64 v[0:1], v[0:1], 0, s[18:19]
	global_load_dwordx4 v[142:145], v[0:1], off
	s_waitcnt vmcnt(7)
	ds_write_b128 v2, v[64:67]
	s_waitcnt vmcnt(6)
	ds_write_b128 v2, v[68:71] offset:4096
	s_waitcnt vmcnt(5)
	ds_write_b128 v2, v[76:79] offset:8192
	s_waitcnt vmcnt(4)
	ds_write_b128 v2, v[84:87] offset:12288
	s_waitcnt vmcnt(3)
	ds_write_b128 v2, v[88:91] offset:16384
	s_waitcnt vmcnt(2)
	ds_write_b128 v2, v[92:95] offset:20480
	s_waitcnt vmcnt(1)
	ds_write_b128 v2, v[128:131] offset:24576
	s_waitcnt vmcnt(0)
	ds_write_b128 v2, v[142:145] offset:28672
	s_or_b64 exec, exec, s[8:9]
